# diff attention: K/V LDS-DMA issue moved into the PV segment at prefetch distance 3 (on v10)
# baseline (speedup 1.0000x reference)
; __device__ __forceinline__ s16x4 vtr(const ALDS unsigned char* p) { return __builtin_bit_cast(s16x4, __builtin_amdgcn_ds_read_tr16_b64_v4i16((ALDS s16x4*)p)); }
; template <int DV, bool BAND> ...
;     ...
;         float ssum = 0.f;
;         bf16x8 pfs[4];
;     ...
;         ATT_EXP_SLICE(p0, 0, pfs[0]);
; #pragma unroll
;         for (int ks = 0; ks < 4; ++ks) {
;             if (ks + 1 < 4) {
; #pragma unroll
;                 for (int db = 0; db < NDB; ++db) { vlo[(ks + 1) & 1][db] = vtr(sb + va[db] + (ks + 1) * (16 * ROWB)); vhh[(ks + 1) & 1][db] = vtr(sb + va[db] + (ks + 1) * (16 * ROWB) + 4 * ROWB); }
;             }
; #pragma unroll
;             for (int db = 0; db < NDB; ++db) {
;                 const s16x4 lo = vlo[ks & 1][db], hh = vhh[ks & 1][db];
;                 const bf16x8 vf = (bf16x8){lo[0], lo[1], lo[2], lo[3], hh[0], hh[1], hh[2], hh[3]};
;                 o[db] = __builtin_amdgcn_mfma_f32_32x32x16_bf16(vf, pfs[ks], o[db], 0, 0, 0);
;             }
;             if (ks == 0) ATT_EXP_SLICE(p0, 8, pfs[1]);
;             if (ks == 1) ATT_EXP_SLICE(p1, 0, pfs[2]);
;             if (ks == 2) ATT_EXP_SLICE(p1, 8, pfs[3]);
;         }
;     ...
;         l += ssum;
;         s_cur = (s_cur == 2 * SLOT) ? 0 : s_cur + SLOT; s_n2 = (s_n2 == 2 * SLOT) ? 0 : s_n2 + SLOT;
.LBB0_773:
	v_exp_f32_e32 v101, v84
	v_exp_f32_e32 v103, v85
	v_exp_f32_e32 v85, v86
	v_exp_f32_e32 v87, v87
	v_exp_f32_e32 v100, v88
	v_exp_f32_e32 v102, v89
	v_exp_f32_e32 v84, v90
	v_exp_f32_e32 v86, v91
	v_cvt_pk_bf16_f32 v88, v101, v103
	v_cvt_pk_bf16_f32 v89, v85, v87
	v_cvt_pk_bf16_f32 v90, v100, v102
	v_cvt_pk_bf16_f32 v91, v84, v86
	ds_read_b64_tr_b16 v[110:111], v108 offset:20480
	ds_read_b64_tr_b16 v[112:113], v108 offset:21504
	ds_read_b64_tr_b16 v[130:131], v107 offset:4096
	ds_read_b64_tr_b16 v[132:133], v107 offset:5120
	ds_read_b64_tr_b16 v[134:135], v106 offset:4096
	ds_read_b64_tr_b16 v[136:137], v106 offset:5120
	ds_read_b64_tr_b16 v[138:139], v67 offset:4096
	ds_read_b64_tr_b16 v[140:141], v67 offset:5120
	s_waitcnt vmcnt(4)
	s_barrier
	s_setprio 0
	s_waitcnt lgkmcnt(14)
	v_mfma_f32_32x32x16_bf16 v[50:65], v[14:17], v[88:91], 0
	v_exp_f32_e32 v105, v92
	v_exp_f32_e32 v93, v93
	v_exp_f32_e32 v104, v94
	v_exp_f32_e32 v92, v95
	ds_read_b64_tr_b16 v[142:143], v108 offset:24576
	ds_read_b64_tr_b16 v[144:145], v108 offset:25600
	ds_read_b64_tr_b16 v[160:161], v107 offset:8192
	ds_read_b64_tr_b16 v[162:163], v107 offset:9216
	ds_read_b64_tr_b16 v[164:165], v106 offset:8192
	ds_read_b64_tr_b16 v[166:167], v106 offset:9216
	ds_read_b64_tr_b16 v[168:169], v67 offset:8192
	ds_read_b64_tr_b16 v[170:171], v67 offset:9216
	v_cvt_pk_bf16_f32 v94, v105, v93
	v_exp_f32_e32 v0, v76
	s_waitcnt lgkmcnt(14)
	v_mfma_f32_32x32x16_bf16 v[34:49], v[10:13], v[88:91], 0
	v_cvt_pk_bf16_f32 v95, v104, v92
	v_exp_f32_e32 v76, v77
	v_exp_f32_e32 v78, v78
	v_exp_f32_e32 v80, v80
	v_exp_f32_e32 v82, v82
	s_add_u32 s8, s90, 0xd8000
	s_addc_u32 s9, s91, 0
	s_add_i32 s13, s30, 0x18000
	s_mov_b32 s14, m0
	s_mov_b32 m0, s13
	s_nop 0
	global_load_lds_dwordx4 v151, s[8:9]
	s_mov_b32 m0, s14
	s_add_u32 s10, s90, 0xd8080
	s_addc_u32 s11, s91, 0
	s_addk_i32 s13, 0x2000
	s_mov_b32 s14, m0
	s_mov_b32 m0, s13
	s_nop 0
	global_load_lds_dwordx4 v151, s[10:11]
	s_mov_b32 m0, s14
	s_add_i32 s10, s84, 0x18000
	s_mov_b32 s11, m0
	s_mov_b32 m0, s10
	s_nop 0
	global_load_lds_dwordx4 v152, s[8:9]
	s_mov_b32 m0, s11
	s_add_u32 s8, s90, 0xdc800
	s_addc_u32 s9, s91, 0
	s_addk_i32 s10, 0x400
	s_mov_b32 s7, m0
	s_mov_b32 m0, s10
	s_nop 0
	global_load_lds_dwordx4 v152, s[8:9]
	s_mov_b32 m0, s7
	s_mov_b32 s4, 1
	s_mov_b32 s5, 0
	v_mfma_f32_32x32x16_bf16 v[18:33], v[2:5], v[88:91], 0
	s_mov_b32 s6, 0x8000
	s_movk_i32 s49, 0x900
	v_mfma_f32_32x32x16_bf16 v[2:17], v[6:9], v[88:91], 0
	v_exp_f32_e32 v89, v96
	v_exp_f32_e32 v91, v97
	v_exp_f32_e32 v88, v98
	v_exp_f32_e32 v90, v99
	v_exp_f32_e32 v99, v68
	v_cvt_pk_bf16_f32 v96, v89, v91
	v_exp_f32_e32 v98, v79
	v_cvt_pk_bf16_f32 v97, v88, v90
	s_nop 1
	v_mfma_f32_32x32x16_bf16 v[50:65], v[110:113], v[94:97], v[50:65]
	v_exp_f32_e32 v113, v69
	v_exp_f32_e32 v112, v83
	v_cvt_pk_bf16_f32 v68, v99, v113
	s_waitcnt lgkmcnt(12)
	v_mfma_f32_32x32x16_bf16 v[34:49], v[130:133], v[94:97], v[34:49]
	s_waitcnt lgkmcnt(10)
	v_mfma_f32_32x32x16_bf16 v[18:33], v[134:137], v[94:97], v[18:33]
	v_exp_f32_e32 v134, v70
	v_exp_f32_e32 v135, v71
	v_exp_f32_e32 v136, v72
	v_exp_f32_e32 v137, v73
	v_cvt_pk_bf16_f32 v69, v134, v135
	v_cvt_pk_bf16_f32 v70, v136, v137
	s_waitcnt lgkmcnt(8)
	v_mfma_f32_32x32x16_bf16 v[2:17], v[138:141], v[94:97], v[2:17]
	v_exp_f32_e32 v138, v74
	v_exp_f32_e32 v139, v75
	ds_read_b64_tr_b16 v[72:73], v108 offset:28672
	ds_read_b64_tr_b16 v[74:75], v108 offset:29696
	ds_read_b64_tr_b16 v[94:95], v107 offset:12288
	ds_read_b64_tr_b16 v[96:97], v107 offset:13312
	ds_read_b64_tr_b16 v[108:109], v106 offset:12288
	ds_read_b64_tr_b16 v[110:111], v106 offset:13312
	ds_read_b64_tr_b16 v[130:131], v67 offset:12288
	ds_read_b64_tr_b16 v[132:133], v67 offset:13312
	v_exp_f32_e32 v106, v81
	v_add_f32_e32 v81, v113, v99
	v_cvt_pk_bf16_f32 v71, v138, v139
	v_add_f32_e32 v107, v135, v134
	v_add_f32_e32 v83, v137, v136
	s_waitcnt lgkmcnt(14)
	v_mfma_f32_32x32x16_bf16 v[50:65], v[142:145], v[68:71], v[50:65]
	v_add_f32_e32 v113, v139, v138
	v_mov_b32_e32 v67, v66
	s_waitcnt lgkmcnt(12)
	v_mfma_f32_32x32x16_bf16 v[34:49], v[160:163], v[68:71], v[34:49]
	s_waitcnt lgkmcnt(10)
	v_mfma_f32_32x32x16_bf16 v[18:33], v[164:167], v[68:71], v[18:33]
	s_waitcnt lgkmcnt(8)
	v_mfma_f32_32x32x16_bf16 v[2:17], v[168:171], v[68:71], v[2:17]
	v_cvt_pk_bf16_f32 v68, v0, v76
	v_cvt_pk_bf16_f32 v69, v78, v98
	v_cvt_pk_bf16_f32 v70, v80, v106
	v_cvt_pk_bf16_f32 v71, v82, v112
	s_waitcnt lgkmcnt(6)
	s_nop 0
	v_mfma_f32_32x32x16_bf16 v[50:65], v[72:75], v[68:71], v[50:65]
	v_add_f32_e64 v72, v102, v100
	v_add_f32_e64 v73, v103, v101
	v_add_f32_e64 v74, v86, v84
	v_add_f32_e64 v75, v87, v85
	v_add_f32_e64 v72, v74, v72
	v_add_f32_e64 v73, v75, v73
	v_pk_add_f32 v[74:75], v[106:107], v[80:81]
	v_pk_add_f32 v[72:73], v[72:73], v[72:73] op_sel_hi:[0,1]
	v_mov_b32_e32 v77, v73
	s_waitcnt lgkmcnt(4)
	v_mfma_f32_32x32x16_bf16 v[34:49], v[94:97], v[68:71], v[34:49]
	v_add_f32_e64 v80, v112, v82
	v_add_f32_e64 v81, v113, v83
	v_mov_b32_e32 v72, v66
	v_add_f32_e64 v74, v80, v74
	v_add_f32_e64 v75, v81, v75
	v_mov_b32_e32 v73, v66
	v_mov_b32_e32 v80, v66
	v_mov_b32_e32 v81, v66
	s_waitcnt lgkmcnt(2)
	v_mfma_f32_32x32x16_bf16 v[18:33], v[108:111], v[68:71], v[18:33]
	s_waitcnt lgkmcnt(0)
	v_mfma_f32_32x32x16_bf16 v[2:17], v[130:133], v[68:71], v[2:17]
	v_add_f32_e64 v68, v92, v104
	v_add_f32_e64 v69, v93, v105
	v_add_f32_e64 v70, v90, v88
	v_add_f32_e64 v71, v91, v89
	v_pk_add_f32 v[68:69], v[68:69], v[68:69] op_sel_hi:[0,1]
	v_pk_add_f32 v[70:71], v[70:71], v[70:71] op_sel_hi:[0,1]
	v_mov_b32_e32 v99, v71
	v_mov_b32_e32 v79, v69
	v_pk_add_f32 v[68:69], v[98:99], v[78:79]
	v_pk_add_f32 v[70:71], v[76:77], v[0:1]
	v_mov_b32_e32 v76, v66
	v_pk_add_f32 v[68:69], v[68:69], v[70:71]
	v_mov_b32_e32 v70, v66
	v_pk_add_f32 v[68:69], v[74:75], v[68:69]
	v_mov_b32_e32 v71, v66
	v_add_f32_e32 v160, v68, v69
	v_mov_b32_e32 v68, v66
	v_mov_b32_e32 v69, v66
	v_mov_b32_e32 v74, v66
	v_mov_b32_e32 v75, v66
	v_mov_b32_e32 v77, v66
	v_mov_b32_e32 v78, v66
	v_mov_b32_e32 v79, v66
	s_branch .LBB0_775
; __device__ __forceinline__ s16x4 vtr(const ALDS unsigned char* p) { return __builtin_bit_cast(s16x4, __builtin_amdgcn_ds_read_tr16_b64_v4i16((ALDS s16x4*)p)); }
; template <int DV, bool BAND> ...
;     ...
;         float ssum = 0.f;
;         bf16x8 pfs[4];
;     ...
;         ATT_EXP_SLICE(p0, 0, pfs[0]);
; #pragma unroll
;         for (int ks = 0; ks < 4; ++ks) {
;             if (ks + 1 < 4) {
; #pragma unroll
;                 for (int db = 0; db < NDB; ++db) { vlo[(ks + 1) & 1][db] = vtr(sb + va[db] + (ks + 1) * (16 * ROWB)); vhh[(ks + 1) & 1][db] = vtr(sb + va[db] + (ks + 1) * (16 * ROWB) + 4 * ROWB); }
;             }
; #pragma unroll
;             for (int db = 0; db < NDB; ++db) {
;                 const s16x4 lo = vlo[ks & 1][db], hh = vhh[ks & 1][db];
;                 const bf16x8 vf = (bf16x8){lo[0], lo[1], lo[2], lo[3], hh[0], hh[1], hh[2], hh[3]};
;                 o[db] = __builtin_amdgcn_mfma_f32_32x32x16_bf16(vf, pfs[ks], o[db], 0, 0, 0);
;             }
;             if (ks == 0) ATT_EXP_SLICE(p0, 8, pfs[1]);
;             if (ks == 1) ATT_EXP_SLICE(p1, 0, pfs[2]);
;             if (ks == 2) ATT_EXP_SLICE(p1, 8, pfs[3]);
;         }
;     ...
;         l += ssum;
;         s_cur = (s_cur == 2 * SLOT) ? 0 : s_cur + SLOT; s_n2 = (s_n2 == 2 * SLOT) ? 0 : s_n2 + SLOT;
.LBB0_774:
	v_exp_f32_e32 v167, v98
	v_exp_f32_e32 v169, v99
	v_exp_f32_e32 v171, v100
	v_exp_f32_e32 v173, v101
	v_exp_f32_e32 v166, v102
	v_exp_f32_e32 v168, v103
	v_exp_f32_e32 v170, v104
	v_exp_f32_e32 v172, v105
	v_cvt_pk_bf16_f32 v98, v167, v169
	v_cvt_pk_bf16_f32 v99, v171, v173
	v_cvt_pk_bf16_f32 v100, v166, v168
	v_cvt_pk_bf16_f32 v101, v170, v172
	ds_read_b64_tr_b16 v[102:103], v164 offset:20480
	ds_read_b64_tr_b16 v[104:105], v164 offset:21504
	s_waitcnt vmcnt(4)
	s_barrier
	s_setprio 0
	s_waitcnt lgkmcnt(8)
	v_mfma_f32_32x32x16_bf16 v[50:65], v[142:145], v[98:101], v[50:65]
	v_exp_f32_e32 v142, v82
	v_exp_f32_e32 v143, v83
	v_exp_f32_e32 v144, v84
	v_exp_f32_e32 v145, v85
	v_exp_f32_e32 v165, v86
	v_exp_f32_e32 v174, v87
	v_exp_f32_e32 v175, v88
	s_waitcnt lgkmcnt(6)
	v_mfma_f32_32x32x16_bf16 v[34:49], v[138:141], v[98:101], v[34:49]
	v_exp_f32_e32 v139, v110
	v_exp_f32_e32 v141, v111
	v_exp_f32_e32 v138, v112
	v_exp_f32_e32 v140, v113
	v_exp_f32_e32 v176, v89
	v_cvt_pk_bf16_f32 v86, v142, v143
	v_cvt_pk_bf16_f32 v87, v144, v145
	s_waitcnt lgkmcnt(4)
	v_mfma_f32_32x32x16_bf16 v[18:33], v[134:137], v[98:101], v[18:33]
	v_exp_f32_e32 v135, v106
	v_exp_f32_e32 v137, v107
	v_exp_f32_e32 v134, v108
	v_exp_f32_e32 v136, v109
	ds_read_b64_tr_b16 v[106:107], v164 offset:24576
	ds_read_b64_tr_b16 v[108:109], v164 offset:25600
	v_cvt_pk_bf16_f32 v88, v165, v174
	v_cvt_pk_bf16_f32 v89, v175, v176
	s_waitcnt lgkmcnt(4)
	v_mfma_f32_32x32x16_bf16 v[2:17], v[130:133], v[98:101], v[2:17]
	v_cvt_pk_bf16_f32 v98, v135, v137
	v_cvt_pk_bf16_f32 v99, v134, v136
	v_cvt_pk_bf16_f32 v100, v139, v141
	v_cvt_pk_bf16_f32 v101, v138, v140
	v_add_f32_e64 v82, v168, v166
	v_add_f32_e64 v83, v169, v167
	v_exp_f32_e32 v0, v90
	v_exp_f32_e32 v90, v94
	s_waitcnt lgkmcnt(2)
	v_mfma_f32_32x32x16_bf16 v[50:65], v[102:105], v[98:101], v[50:65]
	ds_read_b64_tr_b16 v[102:103], v163 offset:4096
	ds_read_b64_tr_b16 v[104:105], v163 offset:5120
	ds_read_b64_tr_b16 v[110:111], v164 offset:29696
	v_exp_f32_e32 v94, v96
	v_exp_f32_e32 v96, v97
	v_add_f32_e32 v97, v176, v175
	s_min_u32 s7, s4, 60
	s_mul_i32 s7, s7, 0x48000
	s_add_u32 s7, s90, s7
	s_addc_u32 s12, s91, 0
	s_add_u32 s8, s7, 0xd8000
	s_addc_u32 s9, s12, 0
	s_add_i32 s13, s5, s30
	s_mov_b32 s10, m0
	s_mov_b32 m0, s13
	s_nop 0
	global_load_lds_dwordx4 v151, s[8:9]
	s_mov_b32 m0, s10
	s_add_u32 s10, s7, 0xd8080
	s_addc_u32 s11, s12, 0
	s_addk_i32 s13, 0x2000
	s_mov_b32 s14, m0
	s_mov_b32 m0, s13
	s_nop 0
	global_load_lds_dwordx4 v151, s[10:11]
	s_mov_b32 m0, s14
	s_add_i32 s10, s5, s84
	s_mov_b32 s11, m0
	s_mov_b32 m0, s10
	s_nop 0
	global_load_lds_dwordx4 v152, s[8:9]
	s_mov_b32 m0, s11
	s_add_u32 s8, s7, 0xdc800
	s_addc_u32 s9, s12, 0
	s_addk_i32 s10, 0x400
	s_mov_b32 s7, m0
	s_mov_b32 m0, s10
	s_nop 0
	global_load_lds_dwordx4 v152, s[8:9]
	s_mov_b32 m0, s7
	s_add_i32 s7, s6, 0x8000
	s_cmp_lg_u32 s6, 0x18000
	s_cselect_b32 s6, s7, 0
	s_waitcnt lgkmcnt(1)
	v_mfma_f32_32x32x16_bf16 v[34:49], v[102:105], v[98:101], v[34:49]
	ds_read_b64_tr_b16 v[102:103], v161 offset:4096
	ds_read_b64_tr_b16 v[104:105], v161 offset:5120
	ds_read_b64_tr_b16 v[130:131], v161 offset:8192
	ds_read_b64_tr_b16 v[132:133], v161 offset:9216
	s_add_i32 s7, s5, 0x8000
	s_cmp_lg_u32 s5, 0x18000
	s_cselect_b32 s5, s7, 0
	s_add_i32 s4, s4, 1
	s_cmp_lg_u32 s4, 64
	s_waitcnt lgkmcnt(2)
	v_mfma_f32_32x32x16_bf16 v[18:33], v[102:105], v[98:101], v[18:33]
	ds_read_b64_tr_b16 v[102:103], v162 offset:4096
	ds_read_b64_tr_b16 v[104:105], v162 offset:5120
	ds_read_b64_tr_b16 v[84:85], v161 offset:13312
	s_waitcnt lgkmcnt(1)
	v_mfma_f32_32x32x16_bf16 v[2:17], v[102:105], v[98:101], v[2:17]
	v_add_f32_e64 v102, v172, v170
	v_add_f32_e64 v103, v173, v171
	v_add_f32_e64 v82, v102, v82
	v_add_f32_e64 v83, v103, v83
	v_mfma_f32_32x32x16_bf16 v[50:65], v[106:109], v[86:89], v[50:65]
	ds_read_b64_tr_b16 v[98:99], v163 offset:8192
	ds_read_b64_tr_b16 v[100:101], v163 offset:9216
	ds_read_b64_tr_b16 v[108:109], v164 offset:28672
	ds_read_b64_tr_b16 v[102:103], v163 offset:12288
	ds_read_b64_tr_b16 v[104:105], v163 offset:13312
	v_pk_add_f32 v[106:107], v[82:83], v[82:83] op_sel_hi:[0,1]
	v_pk_add_f32 v[82:83], v[136:137], v[134:135]
	v_exp_f32_e32 v106, v91
	v_pk_add_f32 v[112:113], v[82:83], v[82:83] op_sel_hi:[0,1]
	v_pk_add_f32 v[82:83], v[140:141], v[138:139]
	s_waitcnt lgkmcnt(3)
	v_mfma_f32_32x32x16_bf16 v[34:49], v[98:101], v[86:89], v[34:49]
	ds_read_b64_tr_b16 v[98:99], v162 offset:8192
	ds_read_b64_tr_b16 v[100:101], v162 offset:9216
	v_add_f32_e64 v134, v82, v82
	v_add_f32_e64 v135, v82, v83
	v_exp_f32_e32 v112, v92
	v_exp_f32_e32 v134, v93
	v_exp_f32_e32 v92, v95
	v_add_f32_e32 v91, v143, v142
	v_add_f32_e32 v93, v145, v144
	v_mfma_f32_32x32x16_bf16 v[18:33], v[130:133], v[86:89], v[18:33]
	ds_read_b64_tr_b16 v[130:131], v162 offset:12288
	ds_read_b64_tr_b16 v[132:133], v162 offset:13312
	ds_read_b64_tr_b16 v[82:83], v161 offset:12288
	v_add_f32_e32 v95, v174, v165
	s_waitcnt lgkmcnt(3)
	v_mfma_f32_32x32x16_bf16 v[2:17], v[98:101], v[86:89], v[2:17]
	v_cvt_pk_bf16_f32 v86, v0, v106
	v_cvt_pk_bf16_f32 v87, v112, v134
	v_cvt_pk_bf16_f32 v88, v90, v92
	v_cvt_pk_bf16_f32 v89, v94, v96
	v_add_f32_e64 v98, v106, v0
	v_add_f32_e64 v99, v107, v1
	v_pk_add_f32 v[100:101], v[134:135], v[112:113]
	v_pk_add_f32 v[90:91], v[92:93], v[90:91]
	v_mfma_f32_32x32x16_bf16 v[50:65], v[108:111], v[86:89], v[50:65]
	v_add_f32_e64 v92, v96, v94
	v_add_f32_e64 v93, v97, v95
	v_add_f32_e64 v98, v100, v98
	v_add_f32_e64 v99, v101, v99
	v_add_f32_e64 v90, v92, v90
	v_add_f32_e64 v91, v93, v91
	v_pk_add_f32 v[90:91], v[90:91], v[98:99]
	s_nop 0
	v_add_f32_e32 v0, v90, v91
	v_mfma_f32_32x32x16_bf16 v[34:49], v[102:105], v[86:89], v[34:49]
	v_add_f32_e32 v160, v160, v0
	s_waitcnt lgkmcnt(0)
	v_mfma_f32_32x32x16_bf16 v[18:33], v[82:85], v[86:89], v[18:33]
	v_mfma_f32_32x32x16_bf16 v[2:17], v[130:133], v[86:89], v[2:17]
	s_cbranch_scc0 .LBB0_777
; #define ALDS __attribute__((address_space(3)))
; __device__ __forceinline__ s16x4 vtr(const ALDS unsigned char* p) { return __builtin_bit_cast(s16x4, __builtin_amdgcn_ds_read_tr16_b64_v4i16((ALDS s16x4*)p)); }
; __device__ __forceinline__ float halfswap_max(float v) { auto rr = __builtin_amdgcn_permlane32_swap(__float_as_uint(v), __float_as_uint(v), false, false); return fmaxf(__uint_as_float(rr[0]), __uint_as_float(rr[1])); }
; template <int DV, bool BAND> ...
;     ...
;     for (int t = t0; t < t1; ++t) {
;         asm volatile("s_waitcnt vmcnt(%0)" :: "n"(NP) : "memory");
;         asm volatile("s_waitcnt lgkmcnt(0)\n\ts_barrier" ::: "memory");
;         const int tn = (t + 2 < t1) ? t + 2 : t1 - 1;
;         const ALDS unsigned char* sb = ring + s_cur;
;         f32x16 p0 = negm, p1 = negm;
;         bf16x8 kf[8];
; #pragma unroll
;         for (int d0 = 0; d0 < 4; ++d0) { kf[2 * d0] = *(const ALDS bf16x8*)(sb + ka + d0 * 2048); kf[2 * d0 + 1] = *(const ALDS bf16x8*)(sb + ka + d0 * 2048 + 512); }
;         s16x4 vlo[2][NDB], vhh[2][NDB];
; #pragma unroll
;         for (int db = 0; db < NDB; ++db) { vlo[0][db] = vtr(sb + va[db]); vhh[0][db] = vtr(sb + va[db] + 4 * ROWB); }
; #pragma unroll
;         for (int d0 = 0; d0 < 4; ++d0) {
;             p0 = __builtin_amdgcn_mfma_f32_32x32x16_bf16(kf[2 * d0], qr[d0], p0, 0, 0, 0);
;             p1 = __builtin_amdgcn_mfma_f32_32x32x16_bf16(kf[2 * d0 + 1], qr[d0], p1, 0, 0, 0);
;         }
;         __builtin_amdgcn_sched_barrier(0);
;         ATT_PIECE(0, tn, s_n2); ATT_PIECE(1, tn, s_n2); ATT_PIECE(2, tn, s_n2); ATT_PIECE(3, tn, s_n2);
;         __builtin_amdgcn_sched_barrier(0);
;         if (BAND) {
;             if (t == tq - 2 || t == tq + 2) {
;                 const int rel0 = t * 64 + 8 * hi - qpos;
; #pragma unroll
;                 for (int r = 0; r < 16; ++r) { const int rel = rel0 + 16 * (r >> 3) + (r & 7);
;                     if (rel < -128 || rel > 128) p0[r] = -INFINITY;
;                     if (rel + 32 < -128 || rel + 32 > 128) p1[r] = -INFINITY; }
;             }
;         }
;         float mx = fmaxf(p0[0], p1[0]);
; #pragma unroll
;         for (int r = 1; r < 16; ++r) mx = fmaxf(fmaxf(mx, p0[r]), p1[r]);
;         mx = halfswap_max(mx);
;         const bool first = (!BAND) && (t == t0);
;         const float dl = first ? mx : ((mx > THR) ? mx : 0.f);
;         if (__any(dl != 0.f)) {
.LBB0_775:
	s_add_i32 s7, s6, 0
	s_waitcnt vmcnt(8)
	s_add_i32 s8, s7, s67
	s_waitcnt lgkmcnt(0)
	s_barrier
	s_setprio 1
	v_add3_u32 v0, s8, v153, v154
	ds_read_b128 v[82:85], v0
	ds_read_b128 v[130:133], v0 offset:512
	v_add_u32_e32 v164, s7, v155
	s_waitcnt lgkmcnt(1)
	v_mfma_f32_32x32x16_bf16 v[98:113], v[82:85], v[114:117], v[66:81]
	v_add_u32_e32 v161, s7, v157
	v_add_u32_e32 v163, s7, v156
	s_waitcnt lgkmcnt(0)
	v_mfma_f32_32x32x16_bf16 v[82:97], v[130:133], v[114:117], v[66:81]
	ds_read_b128 v[130:133], v0 offset:2048
	ds_read_b128 v[134:137], v0 offset:2560
	v_add_u32_e32 v162, s7, v158
	s_waitcnt lgkmcnt(1)
	v_mfma_f32_32x32x16_bf16 v[98:113], v[130:133], v[118:121], v[98:113]
	s_waitcnt lgkmcnt(0)
	v_mfma_f32_32x32x16_bf16 v[82:97], v[134:137], v[118:121], v[82:97]
	ds_read_b128 v[130:133], v0 offset:4096
	ds_read_b128 v[134:137], v0 offset:4608
	ds_read_b128 v[166:169], v0 offset:6656
	s_waitcnt lgkmcnt(2)
	v_mfma_f32_32x32x16_bf16 v[98:113], v[130:133], v[122:125], v[98:113]
	ds_read_b128 v[130:133], v0 offset:6144
	ds_read_b64_tr_b16 v[142:143], v164 offset:16384
	ds_read_b64_tr_b16 v[144:145], v164 offset:17408
	ds_read_b64_tr_b16 v[138:139], v163
	ds_read_b64_tr_b16 v[140:141], v163 offset:1024
	s_waitcnt lgkmcnt(6)
	v_mfma_f32_32x32x16_bf16 v[82:97], v[134:137], v[122:125], v[82:97]
	s_waitcnt lgkmcnt(4)
	v_mfma_f32_32x32x16_bf16 v[98:113], v[130:133], v[126:129], v[98:113]
	ds_read_b64_tr_b16 v[134:135], v161
	ds_read_b64_tr_b16 v[136:137], v161 offset:1024
	ds_read_b64_tr_b16 v[130:131], v162
	ds_read_b64_tr_b16 v[132:133], v162 offset:1024
	v_mfma_f32_32x32x16_bf16 v[82:97], v[166:169], v[126:129], v[82:97]
	s_nop 12
	v_max_f32_e32 v0, v82, v82
	v_max_f32_e32 v165, v98, v98
	v_max_f32_e32 v0, v165, v0
	v_max3_f32 v0, v0, v99, v83
	v_max3_f32 v0, v0, v100, v84
	v_max3_f32 v0, v0, v101, v85
	v_max3_f32 v0, v0, v102, v86
	v_max3_f32 v0, v0, v103, v87
	v_max3_f32 v0, v0, v104, v88
	v_max3_f32 v0, v0, v105, v89
	v_max3_f32 v0, v0, v106, v90
	v_max3_f32 v0, v0, v107, v91
	v_max3_f32 v0, v0, v108, v92
	v_max3_f32 v0, v0, v109, v93
	v_max3_f32 v0, v0, v110, v94
	v_max3_f32 v0, v0, v111, v95
	v_max3_f32 v0, v0, v112, v96
	v_max3_f32 v0, v0, v113, v97
	v_mov_b32_e32 v165, v0
	s_nop 1
	v_permlane32_swap_b32_e32 v0, v165
	v_max_f32_e32 v165, v165, v165
	v_max_f32_e32 v0, v0, v0
	v_max_f32_e32 v0, v0, v165
	v_cmp_lt_f32_e32 vcc, s31, v0
	s_cbranch_vccz .LBB0_774
	s_nop 1
	v_cndmask_b32_e32 v0, 0, v0, vcc
	s_nop 0
	v_exp_f32_e64 v68, -v0
	v_add_f32_e32 v159, v159, v0
	v_xor_b32_e32 v66, 0x80000000, v159
	v_pk_add_f32 v[98:99], v[98:99], v[0:1] op_sel_hi:[1,0] neg_lo:[0,1] neg_hi:[0,1]
	v_pk_add_f32 v[82:83], v[82:83], v[0:1] op_sel_hi:[1,0] neg_lo:[0,1] neg_hi:[0,1]
	v_pk_add_f32 v[100:101], v[100:101], v[0:1] op_sel_hi:[1,0] neg_lo:[0,1] neg_hi:[0,1]
	v_pk_add_f32 v[84:85], v[84:85], v[0:1] op_sel_hi:[1,0] neg_lo:[0,1] neg_hi:[0,1]
	v_pk_add_f32 v[102:103], v[102:103], v[0:1] op_sel_hi:[1,0] neg_lo:[0,1] neg_hi:[0,1]
	v_pk_add_f32 v[86:87], v[86:87], v[0:1] op_sel_hi:[1,0] neg_lo:[0,1] neg_hi:[0,1]
	v_pk_add_f32 v[104:105], v[104:105], v[0:1] op_sel_hi:[1,0] neg_lo:[0,1] neg_hi:[0,1]
	v_pk_add_f32 v[88:89], v[88:89], v[0:1] op_sel_hi:[1,0] neg_lo:[0,1] neg_hi:[0,1]
	v_pk_add_f32 v[106:107], v[106:107], v[0:1] op_sel_hi:[1,0] neg_lo:[0,1] neg_hi:[0,1]
	v_pk_add_f32 v[90:91], v[90:91], v[0:1] op_sel_hi:[1,0] neg_lo:[0,1] neg_hi:[0,1]
	v_pk_add_f32 v[108:109], v[108:109], v[0:1] op_sel_hi:[1,0] neg_lo:[0,1] neg_hi:[0,1]
	v_pk_add_f32 v[92:93], v[92:93], v[0:1] op_sel_hi:[1,0] neg_lo:[0,1] neg_hi:[0,1]
	v_pk_add_f32 v[110:111], v[110:111], v[0:1] op_sel_hi:[1,0] neg_lo:[0,1] neg_hi:[0,1]
	v_pk_add_f32 v[94:95], v[94:95], v[0:1] op_sel_hi:[1,0] neg_lo:[0,1] neg_hi:[0,1]
	v_pk_add_f32 v[112:113], v[112:113], v[0:1] op_sel_hi:[1,0] neg_lo:[0,1] neg_hi:[0,1]
	v_pk_add_f32 v[96:97], v[96:97], v[0:1] op_sel_hi:[1,0] neg_lo:[0,1] neg_hi:[0,1]
	v_pk_mul_f32 v[64:65], v[64:65], v[68:69] op_sel_hi:[1,0]
	v_pk_mul_f32 v[62:63], v[62:63], v[68:69] op_sel_hi:[1,0]
	v_pk_mul_f32 v[60:61], v[60:61], v[68:69] op_sel_hi:[1,0]
	v_pk_mul_f32 v[58:59], v[58:59], v[68:69] op_sel_hi:[1,0]
	v_pk_mul_f32 v[56:57], v[56:57], v[68:69] op_sel_hi:[1,0]
	v_pk_mul_f32 v[54:55], v[54:55], v[68:69] op_sel_hi:[1,0]
	v_pk_mul_f32 v[52:53], v[52:53], v[68:69] op_sel_hi:[1,0]
	v_pk_mul_f32 v[50:51], v[50:51], v[68:69] op_sel_hi:[1,0]
	v_pk_mul_f32 v[48:49], v[48:49], v[68:69] op_sel_hi:[1,0]
	v_pk_mul_f32 v[46:47], v[46:47], v[68:69] op_sel_hi:[1,0]
	v_pk_mul_f32 v[44:45], v[44:45], v[68:69] op_sel_hi:[1,0]
	v_pk_mul_f32 v[42:43], v[42:43], v[68:69] op_sel_hi:[1,0]
	v_pk_mul_f32 v[40:41], v[40:41], v[68:69] op_sel_hi:[1,0]
	v_pk_mul_f32 v[38:39], v[38:39], v[68:69] op_sel_hi:[1,0]
	v_pk_mul_f32 v[36:37], v[36:37], v[68:69] op_sel_hi:[1,0]
	v_pk_mul_f32 v[34:35], v[34:35], v[68:69] op_sel_hi:[1,0]
	v_pk_mul_f32 v[32:33], v[32:33], v[68:69] op_sel_hi:[1,0]
	v_pk_mul_f32 v[30:31], v[30:31], v[68:69] op_sel_hi:[1,0]
	v_pk_mul_f32 v[28:29], v[28:29], v[68:69] op_sel_hi:[1,0]
	v_pk_mul_f32 v[26:27], v[26:27], v[68:69] op_sel_hi:[1,0]
	v_pk_mul_f32 v[24:25], v[24:25], v[68:69] op_sel_hi:[1,0]
	v_pk_mul_f32 v[22:23], v[22:23], v[68:69] op_sel_hi:[1,0]
	v_pk_mul_f32 v[20:21], v[20:21], v[68:69] op_sel_hi:[1,0]
	v_pk_mul_f32 v[18:19], v[18:19], v[68:69] op_sel_hi:[1,0]
	v_pk_mul_f32 v[16:17], v[16:17], v[68:69] op_sel_hi:[1,0]
	v_pk_mul_f32 v[14:15], v[14:15], v[68:69] op_sel_hi:[1,0]
	v_pk_mul_f32 v[12:13], v[12:13], v[68:69] op_sel_hi:[1,0]
	v_pk_mul_f32 v[10:11], v[10:11], v[68:69] op_sel_hi:[1,0]
	v_pk_mul_f32 v[8:9], v[8:9], v[68:69] op_sel_hi:[1,0]
	v_pk_mul_f32 v[6:7], v[6:7], v[68:69] op_sel_hi:[1,0]
	v_pk_mul_f32 v[4:5], v[4:5], v[68:69] op_sel_hi:[1,0]
	v_pk_mul_f32 v[2:3], v[2:3], v[68:69] op_sel_hi:[1,0]
	v_mul_f32_e32 v160, v160, v68
	v_mov_b32_e32 v67, v66
	v_mov_b32_e32 v68, v66
	v_mov_b32_e32 v69, v66
	v_mov_b32_e32 v70, v66
	v_mov_b32_e32 v71, v66
	v_mov_b32_e32 v72, v66
	v_mov_b32_e32 v73, v66
	v_mov_b32_e32 v74, v66
	v_mov_b32_e32 v75, v66
	v_mov_b32_e32 v76, v66
	v_mov_b32_e32 v77, v66
	v_mov_b32_e32 v78, v66
	v_mov_b32_e32 v79, v66
	v_mov_b32_e32 v80, v66
	v_mov_b32_e32 v81, v66
	s_branch .LBB0_774
